# conv: XCD-contiguous work assignment (virtual block id) on top of prep_item prefetch
# speedup vs baseline: 1.0148x; 1.0002x over previous
; #define LAS __attribute__((address_space(3)))
; __device__ __forceinline__ unsigned xb_ld(unsigned* p)              { return __hip_atomic_load(p, __ATOMIC_RELAXED, __HIP_MEMORY_SCOPE_AGENT); }
; __device__ __forceinline__ void xcd_barrier_complete(unsigned* bar, unsigned x, unsigned& nloc, unsigned& nx) {
;     ...
;         sum = 0u; cnt = 0u; mine = 0u;
; #pragma unroll
;         for (unsigned j = 0; j < 16; ++j) { const unsigned c = xb_ld(&bar[XB_XCNT(j)]); sum += c; cnt += (c > 0u) ? 1u : 0u; mine = (j == x) ? c : mine; }
; __global__ void __launch_bounds__(512, 2) fwd_megakernel(Params p) {
;     ...
;     const XcdBarrier xb = xcd_barrier_post((unsigned*)(p.ws + WS_BAR), (volatile LAS unsigned*)&xb_words);
;     const int G = gridDim.x, bid = blockIdx.x;
;     float* XC = (float*)(p.ws + WS_XC);
;     bf16_t* H = (bf16_t*)(p.ws + WS_H);
;     bf16_t* BIG = (bf16_t*)(p.ws + WS_BIG);
;     const float* ADA = (const float*)(p.ws + WS_ADA);
;     bf16_t* Y2 = BIG + (size_t)NROW * FF;
;     phase_prep(p, lds);
;     if (p.ws == nullptr) grid.sync();
;     xcd_barrier(xb);
;     for (int l = 0; l < DEPTH; ++l) {
;         const bool last = (l == DEPTH - 1);
;         const float* ada_l = ADA + (size_t)l * 9 * 6144;
;         const float* xl = (l == 0) ? p.in[0] : p.out;
;         const float* xc = (l == 0) ? p.in[2] : XC;
;         const int Mfull = last ? NLAT : NROW;
.LBB0_95:
	v_writelane_b32 v244, s72, 20
	s_nop 1
	v_writelane_b32 v244, s73, 21
	v_writelane_b32 v244, s74, 22
	v_writelane_b32 v244, s75, 23
	v_writelane_b32 v244, s76, 24
	v_writelane_b32 v244, s77, 25
	v_writelane_b32 v244, s78, 26
	v_writelane_b32 v244, s79, 27
	v_writelane_b32 v244, s80, 28
	v_writelane_b32 v244, s81, 29
	v_writelane_b32 v244, s82, 30
	v_writelane_b32 v244, s83, 31
	v_writelane_b32 v244, s84, 32
	v_writelane_b32 v244, s85, 33
	v_writelane_b32 v244, s86, 34
	v_writelane_b32 v244, s87, 35
	s_or_b64 exec, exec, s[0:1]
	s_add_u32 s0, s62, 0x33ad000
	s_addc_u32 s1, s63, 0
	s_add_u32 s76, s62, 0x3bad000
	s_addc_u32 s77, s63, 0
	s_add_u32 s82, s62, 0x7fad000
	v_writelane_b32 v244, s0, 36
	s_addc_u32 s83, s63, 0
	v_lshl_add_u64 v[0:1], v[0:1], 2, s[66:67]
	v_writelane_b32 v244, s1, 37
	s_add_u32 s0, s62, 0x13aad000
	s_addc_u32 s1, s63, 0
	v_writelane_b32 v244, s0, 38
	s_mul_i32 s89, s47, s46
	v_mov_b32_e32 v8, 0
	v_writelane_b32 v244, s1, 39
	s_add_u32 s0, s62, 0x3345000
	s_addc_u32 s1, s63, 0
	v_writelane_b32 v244, s0, 40
	v_mov_b32_e32 v134, 0x358637bd
	v_mov_b32_e32 v176, 1
	v_writelane_b32 v244, s1, 41
	v_mov_b32_e32 v180, 0xbf3a00e3
	v_readlane_b32 s0, v244, 2
	v_readlane_b32 s12, v244, 14
	v_readlane_b32 s1, v244, 3
	v_readlane_b32 s13, v244, 15
	s_add_u32 s0, s12, 0x1000
	s_addc_u32 s1, s13, 0
	v_readlane_b32 s2, v244, 4
	v_readlane_b32 s3, v244, 5
	v_readlane_b32 s4, v244, 6
	v_readlane_b32 s5, v244, 7
	v_readlane_b32 s6, v244, 8
	v_readlane_b32 s7, v244, 9
	v_readlane_b32 s8, v244, 10
	v_readlane_b32 s9, v244, 11
	v_readlane_b32 s10, v244, 12
	v_readlane_b32 s11, v244, 13
	v_readlane_b32 s14, v244, 16
	v_readlane_b32 s15, v244, 17
	v_writelane_b32 v244, s0, 42
	v_mov_b64_e32 v[136:137], 0x76f
	v_mov_b64_e32 v[138:139], 0x770
	v_writelane_b32 v244, s1, 43
	s_lshl_b32 s0, s92, 4
	v_writelane_b32 v244, s0, 44
	s_add_u32 s0, s62, 0x3375000
	s_addc_u32 s1, s63, 0
	v_writelane_b32 v244, s0, 45
	s_cmp_eq_u64 s[60:61], 0
	v_mov_b32_e32 v186, 0xa0
	v_writelane_b32 v244, s1, 46
	s_cselect_b64 s[0:1], -1, 0
	s_lshl_b32 s33, s46, 4
	s_add_u32 s78, s62, 0x1f9ed200
	v_writelane_b32 v244, s0, 47
	s_addc_u32 s79, s63, 0
	s_nop 0
	v_writelane_b32 v244, s1, 48
	s_add_u32 s0, s62, 0x1f9ed400
	s_addc_u32 s1, s63, 0
	v_writelane_b32 v244, s0, 49
	s_barrier
	s_nop 0
	v_writelane_b32 v244, s1, 50
	s_add_u32 s0, s62, 0x1f9ed500
	s_addc_u32 s1, s63, 0
	v_writelane_b32 v244, s0, 51
	s_nop 1
	v_writelane_b32 v244, s1, 52
	s_add_u32 s0, s62, 0x1f9ed600
	s_addc_u32 s1, s63, 0
	v_writelane_b32 v244, s0, 53
	s_nop 1
	v_writelane_b32 v244, s1, 54
	s_add_u32 s0, s62, 0x1f9ed700
	s_addc_u32 s1, s63, 0
	v_writelane_b32 v244, s0, 55
	s_nop 1
	v_writelane_b32 v244, s1, 56
	s_add_u32 s0, s62, 0x1f9ed800
	s_addc_u32 s1, s63, 0
	v_writelane_b32 v244, s0, 57
	s_nop 1
	v_writelane_b32 v244, s1, 58
	s_add_u32 s0, s62, 0x1f9ed900
	s_addc_u32 s1, s63, 0
	v_writelane_b32 v244, s0, 59
	s_nop 1
	v_writelane_b32 v244, s1, 60
	s_mov_b64 s[0:1], 0x1400
	v_lshl_add_u64 v[130:131], v[0:1], 0, s[0:1]
	s_mov_b64 s[0:1], 0x2400
	v_lshl_add_u64 v[132:133], v[0:1], 0, s[0:1]
	s_add_u32 s0, s62, 0x1f9eda00
	s_addc_u32 s1, s63, 0
	v_writelane_b32 v244, s0, 61
	s_nop 1
	v_writelane_b32 v244, s1, 62
	s_add_u32 s0, s62, 0x1f9edb00
	s_addc_u32 s1, s63, 0
	v_writelane_b32 v244, s0, 63
	s_nop 1
	v_writelane_b32 v243, s1, 0
	s_add_u32 s0, s62, 0x1f9edc00
	s_addc_u32 s1, s63, 0
	s_add_u32 s36, s62, 0x1f9edd00
	s_addc_u32 s37, s63, 0
	s_add_u32 s96, s62, 0x1f9ede00
	s_addc_u32 s97, s63, 0
	s_add_u32 s24, s62, 0x1f9edf00
	s_addc_u32 s25, s63, 0
	s_add_u32 s26, s62, 0x1f9ee000
	s_addc_u32 s27, s63, 0
	s_add_u32 s28, s62, 0x1f9ee100
	s_addc_u32 s29, s63, 0
	s_add_u32 s30, s62, 0x1f9ee200
	s_addc_u32 s31, s63, 0
	s_add_u32 s34, s62, 0x1f9ee300
	s_addc_u32 s35, s63, 0
	v_writelane_b32 v243, s0, 1
	s_cmp_eq_u32 s64, 15
	s_nop 0
	v_writelane_b32 v243, s1, 2
	s_cselect_b64 s[0:1], -1, 0
	v_writelane_b32 v243, s0, 3
	s_cmp_eq_u32 s64, 14
	s_nop 0
	v_writelane_b32 v243, s1, 4
	s_cselect_b64 s[0:1], -1, 0
	v_writelane_b32 v243, s0, 5
	s_cmp_eq_u32 s64, 13
	s_nop 0
	v_writelane_b32 v243, s1, 6
	s_cselect_b64 s[0:1], -1, 0
	v_writelane_b32 v243, s0, 7
	s_cmp_eq_u32 s64, 12
	s_nop 0
	v_writelane_b32 v243, s1, 8
	s_cselect_b64 s[0:1], -1, 0
	v_writelane_b32 v243, s0, 9
	s_cmp_eq_u32 s64, 11
	s_nop 0
	v_writelane_b32 v243, s1, 10
	s_cselect_b64 s[0:1], -1, 0
	v_writelane_b32 v243, s0, 11
	s_cmp_eq_u32 s64, 10
	s_nop 0
	v_writelane_b32 v243, s1, 12
	s_cselect_b64 s[0:1], -1, 0
	v_writelane_b32 v243, s0, 13
	s_cmp_eq_u32 s64, 9
	s_nop 0
	v_writelane_b32 v243, s1, 14
	s_cselect_b64 s[0:1], -1, 0
	v_writelane_b32 v243, s0, 15
	s_cmp_eq_u32 s64, 8
	s_nop 0
	v_writelane_b32 v243, s1, 16
	s_cselect_b64 s[0:1], -1, 0
	v_writelane_b32 v243, s0, 17
	s_cmp_eq_u32 s64, 7
	s_nop 0
	v_writelane_b32 v243, s1, 18
	s_cselect_b64 s[0:1], -1, 0
	v_writelane_b32 v243, s0, 19
	s_cmp_eq_u32 s64, 6
	s_nop 0
	v_writelane_b32 v243, s1, 20
	s_cselect_b64 s[0:1], -1, 0
	v_writelane_b32 v243, s0, 21
	s_cmp_eq_u32 s64, 5
	s_nop 0
	v_writelane_b32 v243, s1, 22
	s_cselect_b64 s[0:1], -1, 0
	v_writelane_b32 v243, s0, 23
	s_cmp_eq_u32 s64, 4
	s_nop 0
	v_writelane_b32 v243, s1, 24
	s_cselect_b64 s[0:1], -1, 0
	v_writelane_b32 v243, s0, 25
	s_cmp_eq_u32 s64, 3
	s_nop 0
	v_writelane_b32 v243, s1, 26
	s_cselect_b64 s[0:1], -1, 0
	v_writelane_b32 v243, s0, 27
	s_cmp_eq_u32 s64, 2
	s_nop 0
	v_writelane_b32 v243, s1, 28
	s_cselect_b64 s[0:1], -1, 0
	v_writelane_b32 v243, s0, 29
	s_cmp_eq_u32 s64, 1
	s_nop 0
	v_writelane_b32 v243, s1, 30
	s_cselect_b64 s[0:1], -1, 0
	v_writelane_b32 v243, s0, 31
	s_cmp_eq_u32 s64, 0
	s_nop 0
; #define LAS __attribute__((address_space(3)))
; __device__ __forceinline__ size_t PIX(int row, int col) { return (size_t)(col >> 7) * PSLOT + (size_t)row * 128 + (col & 127); }
; __device__ __forceinline__ int opaque_tid() { int t = threadIdx.x; asm volatile("" : "+v"(t)); return t; }
; __device__ void scan_chain(const Params& p, int l, int chain, int vhalf, LAS unsigned char* lds) {
;     const int tid = opaque_tid(), w = __builtin_amdgcn_readfirstlane(tid >> 6), lane = tid & 63, l15 = lane & 15, q4 = lane >> 4;
;     const int dir = chain & 1, h = (chain >> 1) & 3, b = chain >> 3;
;     bf16_t* P = (bf16_t*)(p.ws + WS_BIG);
;     auto chunk_of = [&](int s) -> int { return dir ? (s < 8 ? 7 - s : 143 - s) : s; };
;     auto row0_of = [&](int c) -> int { return c < 8 ? NLAT + b * 256 + 32 * c : b * 4096 + 32 * (c - 8); };
;     bf16_t* qb = dir ? (bf16_t*)(p.ws + WS_QB) + (size_t)h * PSLOT : P + PIX(0, 1536 + h * 128);
;     const int qpitch = 128;
;     if (w >= 4) {
;         const int lw = w - 4;
;         const int r16 = lane >> 4, s16 = lane & 15;
;         size_t qoff[2], koff[2];
; #pragma unroll
;         for (int i = 0; i < 2; ++i) { const int row = 8 * lw + 4 * i + r16; qoff[i] = (size_t)row * qpitch + ((s16 ^ (row & 15)) * 8);
;             koff[i] = PIX(4 * (2 * lw + i) + r16, dir * 512 + h * 128) + s16 * 8; }
;         const size_t voff = PIX(16 * vhalf + 4 * lw + r16, 1024 + h * 128) + s16 * 8;
;         const float* dsrc = (const float*)(p.ws + WS_DS) + (size_t)chain * NCH * 128 + (lw & 1) * 64 + lane;
;         const int orow = 8 * lw + (lane >> 3);
;         const size_t ooff = (size_t)h * PSLOT + (size_t)orow * 128 + 64 * vhalf + (((lane & 7) ^ (orow & 7)) * 8);
;         const bf16_t* OFBc = (const bf16_t*)(p.ws + WS_OFB) + (size_t)dir * NROW * 512;
	v_writelane_b32 v243, s1, 32
	s_cselect_b64 s[0:1], -1, 0
	v_writelane_b32 v243, s0, 33
	s_nop 1
	v_writelane_b32 v243, s1, 34
	s_add_u32 s0, s62, 0x1f9f0400
	s_addc_u32 s1, s63, 0
	v_writelane_b32 v243, s0, 35
	s_nop 1
	v_writelane_b32 v243, s1, 36
	s_add_u32 s0, s62, 0x1f9f0500
	s_addc_u32 s1, s63, 0
	v_writelane_b32 v243, s0, 37
	s_cmpk_lt_i32 s92, 0x770
	s_nop 0
	v_writelane_b32 v243, s1, 38
	s_cselect_b64 s[0:1], -1, 0
	v_writelane_b32 v243, s0, 39
	s_ashr_i32 s73, s92, 31
	s_ashr_i32 s21, s46, 31
	v_writelane_b32 v243, s1, 40
	s_lshr_b32 s0, s73, 29
	s_add_i32 s0, s92, s0
	s_ashr_i32 s87, s0, 3
	s_and_b32 s0, s0, -8
	s_sub_i32 s80, s92, s0
	s_cmpk_lt_i32 s92, 0x1100
	s_cselect_b64 s[0:1], -1, 0
	v_writelane_b32 v243, s0, 41
	s_add_u32 s85, s62, 0x33ac000
	s_nop 0
	v_writelane_b32 v243, s1, 42
	s_addc_u32 s0, s63, 0
	s_add_u32 s4, s62, 0x1f5ad000
	s_addc_u32 s14, s63, 0
	v_writelane_b32 v243, s0, 43
	s_add_u32 s0, s62, 0x33ac800
	v_writelane_b32 v243, s0, 44
	s_addc_u32 s0, s63, 0
	s_add_u32 s9, s62, 0x1b1ad000
	s_addc_u32 s10, s63, 0
	s_add_u32 s16, s62, 0x16dad000
	s_addc_u32 s17, s63, 0
	v_writelane_b32 v243, s0, 45
	s_add_u32 s0, s62, 0x18fad000
	s_addc_u32 s1, s63, 0
	v_writelane_b32 v243, s0, 46
	s_cmpk_lt_i32 s46, 0x81
	s_nop 0
	v_writelane_b32 v243, s1, 47
	s_cselect_b64 s[0:1], -1, 0
	v_writelane_b32 v243, s0, 48
	s_cmpk_lt_i32 s92, 0x80
	s_nop 0
	v_writelane_b32 v243, s1, 49
	s_cselect_b64 s[0:1], -1, 0
	v_writelane_b32 v243, s0, 50
	s_cmpk_gt_i32 s92, 0x7f
	s_nop 0
	v_writelane_b32 v243, s1, 51
	s_cselect_b64 s[0:1], -1, 0
	v_writelane_b32 v243, s0, 52
	s_nop 1
	v_writelane_b32 v243, s1, 53
	s_add_u32 s0, s62, 0x3300000
	s_addc_u32 s1, s63, 0
	v_writelane_b32 v243, s0, 54
	s_cmpk_lt_i32 s92, 0x840
	s_nop 0
	v_writelane_b32 v243, s1, 55
	s_cselect_b64 s[0:1], -1, 0
	v_writelane_b32 v243, s0, 56
	s_nop 1
	v_writelane_b32 v243, s1, 57
	s_add_i32 s0, s92, 0x480
	v_writelane_b32 v243, s0, 58
	s_add_u32 s0, s62, 0x2800000
	s_addc_u32 s1, s63, 0
	v_writelane_b32 v243, s0, 59
	s_nop 1
	v_writelane_b32 v243, s1, 60
	s_add_u32 s0, s62, 0x1200000
	s_addc_u32 s1, s63, 0
	v_writelane_b32 v243, s0, 61
	s_nop 1
	v_writelane_b32 v243, s1, 62
	s_add_u32 s0, s62, 0xe00000
	s_addc_u32 s1, s63, 0
	v_writelane_b32 v243, s0, 63
	s_nop 1
	v_writelane_b32 v242, s1, 0
	s_add_i32 s0, s92, 0xffffff80
	v_writelane_b32 v242, s0, 1
	s_add_i32 s0, s46, 0xffffff80
	s_cmpk_lt_u32 s92, 0x8c0
	v_writelane_b32 v242, s0, 2
	s_cselect_b64 s[0:1], -1, 0
	v_writelane_b32 v242, s0, 3
	s_bfe_u32 s5, s92, 0x20001
	s_mul_i32 s7, s5, 0x440000
	v_writelane_b32 v242, s1, 4
	s_ashr_i32 s0, s92, 1
	s_and_b32 s0, s0, -8
	s_and_b32 s1, s92, 7
	s_or_b32 s0, s0, s1
	s_add_i32 s1, s92, 0x400
	v_writelane_b32 v242, s1, 5
	s_bfe_u32 s1, s92, 0x10003
	s_and_b32 s3, s92, 1
	s_bfe_i32 s6, s92, 0x10000
	s_ashr_i32 s15, s92, 4
	s_lshl_b32 s8, s7, 1
	v_writelane_b32 v242, s9, 6
	s_add_u32 s9, s9, s8
	v_writelane_b32 v242, s10, 7
	s_addc_u32 s10, s10, 0
	s_add_u32 s11, s82, s8
	s_addc_u32 s12, s83, 0
	s_add_u32 s11, s11, 0x6600000
	s_addc_u32 s12, s12, 0
	s_lshl_b32 s18, s1, 6
	s_mul_i32 s13, s3, 0x2200000
	s_add_u32 s64, s16, s13
	v_writelane_b32 v242, s16, 8
	s_addc_u32 s65, s17, 0
	s_add_u32 s8, s64, s8
	v_writelane_b32 v242, s17, 9
	v_writelane_b32 v242, s8, 10
	s_addc_u32 s8, s65, 0
	v_writelane_b32 v242, s8, 11
	s_lshl_b32 s8, s3, 2
	s_lshl_b32 s1, s1, 4
	s_or_b32 s23, s8, s5
	v_writelane_b32 v242, s1, 12
	s_mul_hi_i32 s1, s0, 0x11000
	s_mul_i32 s0, s0, 0x11000
	s_add_i32 s86, s7, 0x2200000
	v_writelane_b32 v242, s4, 13
	s_add_u32 s0, s4, s0
	v_writelane_b32 v242, s0, 14
	v_writelane_b32 v242, s14, 15
	s_addc_u32 s0, s14, s1
	v_writelane_b32 v242, s0, 16
	s_and_b32 s6, s6, 7
	s_lshl_b32 s0, s15, 8
	s_add_i32 s8, s0, 0x8000
	s_lshl_b32 s0, s6, 5
	s_or_b32 s0, s0, s8
	s_ashr_i32 s1, s0, 31
	s_lshl_b64 s[0:1], s[0:1], 8
	s_or_b32 s88, s7, s18
	v_writelane_b32 v242, s15, 17
	s_add_u32 s4, s82, s0
	v_writelane_b32 v242, s18, 18
	s_addc_u32 s5, s83, s1
	v_writelane_b32 v242, s4, 19
	s_lshl_b32 s90, s6, 9
	s_nop 0
	v_writelane_b32 v242, s5, 20
	s_add_u32 s4, s64, s0
	s_addc_u32 s5, s65, s1
	v_writelane_b32 v242, s4, 21
	s_cmp_eq_u32 s3, 0
	s_nop 0
	v_writelane_b32 v242, s5, 22
	s_cselect_b64 s[4:5], -1, 0
	v_writelane_b32 v242, s4, 23
	s_and_b64 s[6:7], s[4:5], exec
	s_cselect_b32 s81, s11, s9
	s_cselect_b32 s9, 1, 6
	s_cselect_b32 s84, s12, s10
	s_cselect_b32 s10, 2, 5
	s_cselect_b32 s11, 5, 2
	s_cselect_b32 s12, 6, 1
	s_cselect_b32 s13, 7, 0
	s_lshl_b32 s6, s9, 5
	s_or_b32 s6, s6, s8
	s_ashr_i32 s7, s6, 31
	s_lshl_b64 s[38:39], s[6:7], 8
	v_writelane_b32 v242, s5, 24
	s_add_u32 s4, s82, s38
	s_addc_u32 s5, s83, s39
	v_writelane_b32 v242, s4, 25
	s_lshl_b32 s94, s9, 9
	s_nop 0
	v_writelane_b32 v242, s5, 26
	s_add_u32 s4, s64, s38
	s_addc_u32 s5, s65, s39
	s_lshl_b32 s6, s10, 5
	s_or_b32 s6, s6, s8
	s_ashr_i32 s7, s6, 31
	v_writelane_b32 v242, s4, 27
	s_lshl_b64 s[40:41], s[6:7], 8
	s_nop 0
	v_writelane_b32 v242, s5, 28
	s_add_u32 s4, s82, s40
	s_addc_u32 s5, s83, s41
	v_writelane_b32 v242, s4, 29
	s_lshl_b32 vcc_lo, s10, 9
	s_nop 0
	v_writelane_b32 v242, s5, 30
	s_add_u32 s4, s64, s40
	s_addc_u32 s5, s65, s41
	s_add_i32 s9, s3, 3
	s_lshl_b32 s6, s9, 5
	s_or_b32 s6, s8, s6
	s_ashr_i32 s7, s6, 31
	v_writelane_b32 v242, s4, 31
	s_lshl_b64 s[42:43], s[6:7], 8
	s_nop 0
	v_writelane_b32 v242, s5, 32
	s_add_u32 s4, s82, s42
	s_addc_u32 s5, s83, s43
	v_writelane_b32 v242, s4, 33
	s_lshl_b32 s74, s9, 9
	s_nop 0
	v_writelane_b32 v242, s5, 34
	s_add_u32 s4, s64, s42
	s_addc_u32 s5, s65, s43
	s_sub_i32 s3, 4, s3
	s_lshl_b32 s6, s3, 5
	s_or_b32 s6, s8, s6
	s_ashr_i32 s7, s6, 31
;     __device__ bool next(int i, Unit& u) const {
;         const long L = (long)i * G + c; if (L >= nwg) return false;
;         int wgid = (int)L; { const int q = nwg / NXCD, r = nwg % NXCD, xcd = wgid % NXCD, off = wgid / NXCD; wgid = (xcd < r ? xcd * (q + 1) : r * (q + 1) + (xcd - r) * q) + off; }
;         const int nig = WGM * nN, gid = wgid / nig, fm = gid * WGM, gsz = (nM - fm) < WGM ? (nM - fm) : WGM;
;         u.pm = fm + ((wgid % nig) % gsz); u.pn = (wgid % nig) / gsz; return true;
;     }
; __device__ void phase_conv(const Params& p, int l, int nrows) {
;     ...
;     const long total = (long)(nrows / 16) * 352;
;     for (long id0 = (long)blockIdx.x * 512 + tid_; id0 < total; id0 += (long)gridDim.x * 512) {
	v_writelane_b32 v242, s4, 35
	s_lshl_b64 s[44:45], s[6:7], 8
	s_nop 0
	v_writelane_b32 v242, s5, 36
	s_add_u32 s4, s82, s44
	s_addc_u32 s5, s83, s45
	v_writelane_b32 v242, s4, 37
	s_lshl_b32 s72, s3, 9
	s_nop 0
	v_writelane_b32 v242, s5, 38
	s_add_u32 s4, s64, s44
	v_writelane_b32 v242, s64, 39
	s_addc_u32 s5, s65, s45
	s_lshl_b32 s3, s11, 5
	v_writelane_b32 v242, s65, 40
	s_or_b32 s6, s8, s3
	v_writelane_b32 v242, s4, 41
	s_ashr_i32 s7, s6, 31
	s_lshl_b64 s[64:65], s[6:7], 8
	v_writelane_b32 v242, s5, 42
	s_lshl_b64 s[4:5], s[6:7], 7
	v_writelane_b32 v242, s4, 43
	s_nop 1
	v_writelane_b32 v242, s5, 44
	s_add_u32 s4, s82, s64
	s_addc_u32 s5, s83, s65
	s_lshl_b32 s3, s12, 5
	s_or_b32 s6, s8, s3
	v_writelane_b32 v242, s4, 45
	s_ashr_i32 s7, s6, 31
	s_lshl_b64 s[66:67], s[6:7], 8
	v_writelane_b32 v242, s5, 46
	s_lshl_b64 s[4:5], s[6:7], 7
	v_writelane_b32 v242, s4, 47
	s_lshl_b32 s68, s11, 9
	s_nop 0
	v_writelane_b32 v242, s5, 48
	s_add_u32 s4, s82, s66
	s_addc_u32 s5, s83, s67
	s_lshl_b32 s3, s13, 5
	s_or_b32 s6, s8, s3
	v_writelane_b32 v242, s4, 49
	s_ashr_i32 s7, s6, 31
	s_lshl_b64 s[70:71], s[6:7], 8
	v_writelane_b32 v242, s5, 50
	s_lshl_b64 s[4:5], s[6:7], 7
	v_writelane_b32 v242, s4, 51
	s_lshl_b32 s22, s12, 9
	s_mov_b32 s3, 0
	v_writelane_b32 v242, s5, 52
	s_add_u32 s4, s82, s70
	s_addc_u32 s5, s83, s71
	v_writelane_b32 v242, s4, 53
	s_mov_b32 s93, s3
	s_mov_b32 s47, s3
	v_writelane_b32 v242, s5, 54
	s_lshl_b32 s4, s46, 5
	v_writelane_b32 v242, s4, 55
	s_and_b32 s4, s92, 7
	s_lshr_b32 s5, s46, 3
	s_mul_i32 s4, s4, s5
	s_lshr_b32 s5, s92, 3
	s_add_u32 s4, s4, s5
	s_and_b32 s5, s46, 7
	s_cmp_eq_u32 s5, 0
	s_cselect_b32 s4, s4, s92
	s_mov_b32 s5, 0
	s_lshl_b64 s[4:5], s[4:5], 9
	v_writelane_b32 v242, s4, 56
	s_lshl_b32 s20, s13, 9
	s_lshl_b32 s2, s92, 5
	v_writelane_b32 v242, s5, 57
	s_lshl_b64 s[4:5], s[46:47], 9
	v_writelane_b32 v242, s4, 58
	s_cmp_lt_i32 s46, 0
	s_mov_b32 s91, s3
	v_writelane_b32 v242, s5, 59
	s_cselect_b64 s[4:5], -1, 0
	v_writelane_b32 v242, s4, 60
	s_cmpk_lt_i32 s92, 0xcc0
	s_mov_b32 s95, s3
	v_writelane_b32 v242, s5, 61
	s_cselect_b64 s[4:5], -1, 0
	v_writelane_b32 v242, s4, 62
	s_mov_b32 vcc_hi, s3
	s_mov_b32 s75, s3
	v_writelane_b32 v242, s5, 63
	s_add_u32 s4, s56, 0xb00000
	s_addc_u32 s5, s57, 0
	v_writelane_b32 v241, s4, 0
	s_mov_b32 s93, s21
	s_mov_b32 s21, s3
	v_writelane_b32 v241, s5, 1
	s_add_u32 s4, s62, 0x2d80000
	s_addc_u32 s5, s63, 0
	v_writelane_b32 v241, s4, 2
	s_mov_b32 s47, 0x800000
	s_nop 0
	v_writelane_b32 v241, s5, 3
	s_add_u32 s4, s50, 0x1600000
	s_addc_u32 s5, s51, 0
	v_writelane_b32 v241, s4, 4
	s_nop 1
	v_writelane_b32 v241, s5, 5
	s_add_u32 s4, s62, 0x1d00000
	s_addc_u32 s5, s63, 0
	v_writelane_b32 v241, s4, 6
	s_nop 1
	v_writelane_b32 v241, s5, 7
	s_add_u32 s4, s48, 0x400000
	s_addc_u32 s5, s49, 0
	v_writelane_b32 v241, s4, 8
	s_nop 1
	v_writelane_b32 v241, s5, 9
	s_add_u32 s4, s62, 0x1000000
	s_addc_u32 s5, s63, 0
	v_writelane_b32 v241, s4, 10
	s_nop 1
	v_writelane_b32 v241, s5, 11
	v_readlane_b32 s4, v244, 20
	v_readlane_b32 s5, v244, 21
	s_add_u32 s4, s4, 0xe00000
	s_addc_u32 s5, s5, 0
	v_writelane_b32 v241, s4, 12
	v_readlane_b32 s6, v244, 22
	v_readlane_b32 s7, v244, 23
	v_writelane_b32 v241, s5, 13
	s_add_u32 s4, s62, 0x700000
	s_addc_u32 s5, s63, 0
	v_writelane_b32 v241, s4, 14
	s_cmp_lt_i32 s80, 0
	v_readlane_b32 s9, v244, 25
	v_writelane_b32 v241, s5, 15
	s_movk_i32 s4, 0xef
	s_cselect_b32 s6, s4, 0xee
	s_mul_i32 s6, s80, s6
	s_add_i32 s6, s6, s87
	s_mul_hi_i32 s7, s6, 0x92492493
	s_add_i32 s7, s7, s6
	s_lshr_b32 s9, s7, 31
	s_ashr_i32 s7, s7, 6
	s_add_i32 s7, s7, s9
	s_mul_i32 s9, s7, 0x70
	s_sub_i32 s6, s6, s9
	s_bfe_i32 s9, s6, 0x80000
	s_bfe_u32 s9, s9, 0x3000c
	v_readlane_b32 s10, v244, 26
	s_add_i32 s9, s6, s9
	s_and_b32 s10, s9, 0xf8
	s_sub_i32 s6, s6, s10
	s_bfe_i32 s9, s9, 0x80000
	s_lshl_b32 s7, s7, 3
	s_sext_i32_i16 s9, s9
	s_sext_i32_i8 s6, s6
	s_add_i32 s10, s7, s6
	s_lshr_b32 s6, s9, 3
	v_writelane_b32 v241, s87, 16
	s_ashr_i32 s4, s9, 3
	s_bfe_i64 s[6:7], s[6:7], 0x100000
	v_writelane_b32 v241, s4, 17
	s_lshl_b64 s[4:5], s[6:7], 19
	v_readlane_b32 s11, v244, 27
	v_writelane_b32 v241, s4, 18
	s_ashr_i32 s11, s10, 31
	s_lshl_b64 s[6:7], s[10:11], 19
	v_writelane_b32 v241, s5, 19
	s_mov_b32 s4, s10
	v_writelane_b32 v241, s4, 20
	s_mov_b32 s87, s3
	v_readlane_b32 s8, v244, 24
	v_writelane_b32 v241, s5, 21
	s_add_u32 s4, s76, s6
	s_addc_u32 s5, s77, s7
	s_add_u32 s6, s4, 0x40000
	v_writelane_b32 v241, s4, 22
	s_addc_u32 s7, s5, 0
	s_add_u32 s0, s81, s0
	v_writelane_b32 v241, s5, 23
	v_writelane_b32 v241, s6, 24
	s_addc_u32 s1, s84, s1
; __device__ __forceinline__ float fast_rcp(float x) { return __builtin_amdgcn_rcpf(x); }
; __device__ __forceinline__ float gelu_f(float v) {
;     const float av = fabsf(v), t = fast_rcp(av * 0.2316418882f + 1.0f);
;     float q = t * 0.5307027145f + (-0.7265760135f); q = q * t + 0.7107068705f; q = q * t + (-0.142248368f); q = q * t + 0.127414796f; q = q * t;
;     const float e = __builtin_amdgcn_exp2f((v * v) * (-0.72134752044f));
;     const float m = v * (q * e);
;     return v < 0.f ? m : v - m;
; }
; __global__ void __launch_bounds__(512, 2) fwd_megakernel(Params p) {
;     ...
;         xcd_barrier(xb);
;         { pg8::StaticOrder S; S.init(Mfull, D, G, bid);
;           pg8::EpiBf16 E{Y2, D, 0, 0, 0};
;           pg8::gemm_phase(lds, pg8::Gemm{BIG, (const bf16_t*)(p.ws + WS_WDOWN) + (size_t)l * D * FF, Mfull, D, FF}, S, E); }
;         if (!last) {
;             const int nwg = (Mfull / 256) * (D / 256), full = (nwg / G) * G, busy = nwg - full;
;             if (busy > 0 && busy < G) { if (bid >= busy) for (int t = bid - busy; t < NT_LAYER; t += G - busy) transpose_tile(p, lds, l + 1, t); }
;             else for (int t = bid; t < NT_LAYER; t += G) transpose_tile(p, lds, l + 1, t);
	s_mov_b64 s[8:9], -1
	v_writelane_b32 v241, s7, 25
	v_writelane_b32 v241, s0, 26
	v_readlane_b32 s12, v244, 28
	v_readlane_b32 s13, v244, 29
	v_writelane_b32 v241, s1, 27
	s_add_u32 s0, s81, s38
	s_addc_u32 s1, s84, s39
	v_writelane_b32 v241, s0, 28
	v_readlane_b32 s14, v244, 30
	v_readlane_b32 s15, v244, 31
	v_writelane_b32 v241, s1, 29
	s_add_u32 s0, s81, s40
	s_addc_u32 s1, s84, s41
	v_writelane_b32 v241, s0, 30
	v_readlane_b32 s16, v244, 32
	v_readlane_b32 s17, v244, 33
	v_writelane_b32 v241, s1, 31
	s_add_u32 s0, s81, s42
	s_addc_u32 s1, s84, s43
	v_writelane_b32 v241, s0, 32
	v_readlane_b32 s18, v244, 34
	v_readlane_b32 s19, v244, 35
	v_writelane_b32 v241, s1, 33
	s_add_u32 s0, s81, s44
	s_addc_u32 s1, s84, s45
	v_writelane_b32 v241, s0, 34
	s_mov_b32 s45, s73
	s_mov_b32 s73, s3
	v_writelane_b32 v241, s1, 35
	s_add_u32 s0, s81, s64
	s_addc_u32 s1, s84, s65
	v_writelane_b32 v241, s0, 36
	s_mul_i32 s65, s89, s69
	s_mov_b32 s89, s3
	v_writelane_b32 v241, s1, 37
	s_add_u32 s0, s81, s66
	s_addc_u32 s1, s84, s67
	v_writelane_b32 v241, s0, 38
	s_mov_b32 s69, s3
	s_mov_b32 s44, 0x3f35f0e3
	v_writelane_b32 v241, s1, 39
	v_writelane_b32 v241, s81, 40
	s_add_u32 s0, s81, s70
	v_writelane_b32 v241, s84, 41
	s_addc_u32 s1, s84, s71
	v_writelane_b32 v241, s0, 42
	s_lshr_b32 s4, s80, 31
	v_readlane_b32 s70, v244, 55
	v_writelane_b32 v241, s1, 43
	s_abs_i32 s0, s46
	v_cvt_f32_u32_e32 v0, s0
	s_sub_i32 s1, 0, s0
	v_writelane_b32 v241, s80, 44
	v_writelane_b32 v241, s4, 45
	v_rcp_iflag_f32_e32 v0, v0
	v_readlane_b32 s4, v242, 60
	v_readlane_b32 s5, v242, 61
	v_readlane_b32 s71, v244, 56
	v_mul_f32_e32 v0, 0x4f7ffffe, v0
	v_cvt_u32_f32_e32 v0, v0
	s_mov_b32 s80, 0x3e6d3388
	s_movk_i32 s81, 0x1600
	s_mov_b32 s84, 0xbe11a98e
	v_readfirstlane_b32 s6, v0
	s_mul_i32 s1, s1, s6
	s_mul_hi_u32 s1, s6, s1
	s_add_i32 s6, s6, s1
	s_mul_hi_u32 s1, s6, 0x220
	s_mul_i32 s1, s1, s0
	s_sub_i32 s1, 0x220, s1
	s_sub_i32 s6, s1, s0
	s_cmp_ge_u32 s1, s0
	s_cselect_b32 s1, s6, s1
	s_sub_i32 s6, s1, s0
	s_cmp_ge_u32 s1, s0
	s_cselect_b32 s6, s6, s1
	s_cmp_eq_u32 s6, 0
	s_cselect_b64 s[0:1], -1, 0
	s_or_b64 s[0:1], s[4:5], s[0:1]
	v_writelane_b32 v241, s0, 46
	s_cmp_ge_i32 s92, s6
	s_mov_b32 s5, 0x87ff
	v_writelane_b32 v241, s1, 47
	s_mul_i32 s0, s23, 0x440000
	v_writelane_b32 v241, s0, 48
	v_writelane_b32 v241, s86, 49
	s_mov_b32 s23, s3
	s_cselect_b64 s[0:1], -1, 0
	v_writelane_b32 v241, s87, 50
	v_writelane_b32 v241, s88, 51
	v_mbcnt_lo_u32_b32 v0, -1, 0
	v_mbcnt_hi_u32_b32 v177, -1, v0
	v_writelane_b32 v241, s89, 52
	v_writelane_b32 v241, s90, 53
	v_and_b32_e32 v0, 64, v177
	v_add_u32_e32 v178, 64, v0
	v_writelane_b32 v241, s91, 54
	v_writelane_b32 v241, s94, 55
	v_xor_b32_e32 v185, 32, v177
	v_xor_b32_e32 v184, 16, v177
	v_writelane_b32 v241, s95, 56
	v_writelane_b32 v241, vcc_lo, 57
	v_xor_b32_e32 v183, 8, v177
	v_xor_b32_e32 v182, 4, v177
	v_writelane_b32 v241, vcc_hi, 58
	v_writelane_b32 v241, s74, 59
	v_xor_b32_e32 v181, 2, v177
	v_xor_b32_e32 v179, 1, v177
	v_writelane_b32 v241, s75, 60
	v_writelane_b32 v241, s72, 61
	s_mov_b32 s87, 0x880000
	s_movk_i32 s91, 0xff00
	v_writelane_b32 v241, s73, 62
	v_writelane_b32 v241, s68, 63
	s_mov_b32 s4, 0xba2e8ba3
	s_mov_b64 s[94:95], 0x80
	v_writelane_b32 v240, s69, 0
	v_writelane_b32 v240, s22, 1
	s_mov_b32 s69, 0xbfb8aa3b
	s_mov_b32 s86, 0x3db504f3
	v_writelane_b32 v240, s23, 2
	v_writelane_b32 v240, s20, 3
	s_mov_b32 s68, 0x3f07dc22
	s_mov_b32 s90, 0xbf3a00e3
	v_writelane_b32 v240, s21, 4
	v_writelane_b32 v240, s0, 5
	s_mov_b32 s64, 0x3e027906
	s_nop 0
	v_writelane_b32 v240, s1, 6
	s_sub_i32 s0, s92, s6
	s_cmpk_lt_i32 s0, 0xcc0
	v_writelane_b32 v240, s0, 7
	s_cselect_b64 s[0:1], -1, 0
	v_writelane_b32 v240, s0, 8
	s_nop 1
	v_writelane_b32 v240, s1, 9
	s_sub_i32 s0, s46, s6
	v_readlane_b32 s1, v244, 44
	v_writelane_b32 v240, s0, 10
	s_sub_i32 s0, 0x87ff, s1
	v_writelane_b32 v240, s0, 11
	s_sub_i32 s0, 0x10ff, s92
	v_writelane_b32 v240, s0, 12
	s_add_i32 s0, s92, 0xfffffa80
	v_writelane_b32 v240, s0, 13
	v_writelane_b32 v240, s2, 14
	s_add_i32 s0, s2, 0xfffff000
	v_writelane_b32 v240, s0, 15
	v_readlane_b32 s0, v242, 55
	s_addk_i32 s0, 0xf000
	s_mov_b32 s2, s3
	v_writelane_b32 v240, s0, 16
	s_sub_i32 s0, 0xffff7ffe, s1
	v_writelane_b32 v240, s0, 17
	s_add_i32 s0, 16, 0x17800
	v_writelane_b32 v240, s0, 18
	s_add_i32 s0, 16, 0x10600
	v_writelane_b32 v240, s0, 19
	s_add_i32 s0, 16, 0x15000
	v_writelane_b32 v242, s0, 60
	s_add_i32 s0, 16, 0x12800
	v_writelane_b32 v240, s0, 20
	v_writelane_b32 v240, s78, 21
	s_nop 1
	v_writelane_b32 v240, s79, 22
	v_writelane_b32 v240, s85, 23
	s_branch .LBB0_98
